# G1 unit order per XCD group: XCDs 0-3 run their light-epilogue units first, XCDs 4-7 their heavy-epilogue units first (same units, permuted order), so epilogue store bursts of the two halves drift apa
# speedup vs baseline: 1.0553x; 1.0095x over previous
.LBB0_185:
	s_and_b64 s[0:1], s[78:79], exec
	v_readlane_b32 s0, v235, 27
	v_readlane_b32 s1, v235, 28
	v_readlane_b32 s6, v236, 12
	s_cselect_b32 s57, s0, s1
	v_readlane_b32 s0, v235, 29
	v_readlane_b32 s1, v235, 30
	v_mov_b32_e32 v8, v194
	v_readlane_b32 s7, v236, 13
	s_cselect_b32 s58, s0, s1
	v_cmp_ne_u32_e64 s[0:1], 1, v196
	s_andn2_b64 vcc, exec, s[6:7]
	v_readfirstlane_b32 s16, v8
	s_cbranch_vccnz .LBB0_187
	s_and_b64 s[8:9], s[78:79], exec
	v_readlane_b32 s6, v234, 19
	s_cselect_b32 s8, 20, 19
	v_readlane_b32 s7, v234, 20
	s_lshl_b64 s[8:9], s[6:7], s8
	s_add_u32 s40, s84, s8
	s_addc_u32 s41, s85, s9
	v_readlane_b32 s8, v234, 22
	v_readlane_b32 s9, v234, 23
	s_add_u32 s42, s58, s8
	s_addc_u32 s43, s57, s9
	v_readlane_b32 s70, v234, 21
	s_bitcmp1_b32 s2, 2
	s_cbranch_scc0 .Lmy_g1ord
	s_add_u32 s42, s42, 0x800000
	s_addc_u32 s43, s43, 0
	s_add_i32 s70, s70, 16
.Lmy_g1ord:
	s_mov_b32 s22, s6

.LBB0_192:
	s_add_i32 s63, s63, 1
	s_lshr_b32 s98, s63, 1
	s_lshr_b32 s99, s63, 2
	s_xor_b32 s98, s98, s99
	s_and_b32 s98, s98, 1
	s_mul_i32 s98, s98, 6
	s_xor_b32 s98, s63, s98
	s_and_b32 s99, s2, 4
	s_lshr_b32 s99, s99, 1
	s_xor_b32 s99, s98, s99
	s_mul_i32 s0, s99, s10
	s_add_i32 s0, s0, s2
	s_cmpk_gt_i32 s0, 0x7ff
	s_cselect_b64 s[46:47], -1, 0
	s_and_b64 vcc, exec, s[46:47]
	s_cbranch_vccnz .LBB0_198
	s_ashr_i32 s1, s0, 31
	s_lshr_b32 s1, s1, 29
	s_add_i32 s23, s0, s1
	s_and_b32 s1, s23, -8
	s_sub_i32 s24, s0, s1
	s_cmp_gt_i32 s24, -1
	s_mov_b64 s[0:1], -1
	s_cbranch_scc0 .LBB0_195
	s_lshl_b32 s25, s24, 8
	s_mov_b64 s[0:1], 0
